# MLA body B (waves 4-7) reordered: staging writes, softmax finish, loads, QK, bare PV, softmax (amplified A/B: about -7 us per attention pass vs previous body B)
# speedup vs baseline: 1.0071x; 1.0071x over previous
; __device__ __forceinline__ void finishSM(f32x16& p0, f32x16& p1, float alpha, float& l_reg, bf16x8& pa0, bf16x8& pa1, bf16x8& pa2, bf16x8& pa3) {
; #pragma unroll
;   for (int r = 0; r < 16; ++r) p1[r] = __builtin_amdgcn_exp2f(p1[r]);
;   float ps = 0;
; #pragma unroll
;   for (int r = 0; r < 16; ++r) ps += p0[r];
; #pragma unroll
;   for (int r = 0; r < 16; ++r) ps += p1[r];
;   { auto rr = __builtin_amdgcn_permlane32_swap(__float_as_uint(ps), __float_as_uint(ps), false, false);
;     ps = __uint_as_float(rr[0]) + __uint_as_float(rr[1]); }
;   l_reg = l_reg * alpha + ps;
;     ...
;   PK4(p0, 0, pa0); PK4(p0, 8, pa1); PK4(p1, 0, pa2); PK4(p1, 8, pa3);
;     ...
; }
; template <int DQK> __device__ __forceinline__ void qkt(f32x16& p0, f32x16& p1, const char* Ks, const bf16x8* qr, int r32, int hi) {
;   p0 = f32x16{}; p1 = f32x16{};
; #pragma unroll
;   for (int d0 = 0; d0 < DQK / 16; ++d0) { int cb = (d0 * 16 + hi * 8) * 2;
;     bf16x8 b0 = *reinterpret_cast<const bf16x8*>(Ks + KSWZ(r32, cb));
;     bf16x8 b1 = *reinterpret_cast<const bf16x8*>(Ks + KSWZ(32 + r32, cb));
;     p0 = __builtin_amdgcn_mfma_f32_32x32x16_bf16(b0, qr[d0], p0, 0, 0, 0);
;     p1 = __builtin_amdgcn_mfma_f32_32x32x16_bf16(b1, qr[d0], p1, 0, 0, 0); }
; }
; __device__ __forceinline__ int v_st(int k, int c) { const int kk = (k & ~0xC) | ((k & 4) << 1) | ((k & 8) >> 1); return ((kk >> 3) * 4 + (c >> 5)) * 512 + ((kk & 7) * 32 + (c & 31)) * 2; }
; __device__ __forceinline__ int v_rd_base(int lane) { return ((lane & 3) << 3) | (((lane >> 2) & 3) << 6) | (((lane >> 4) & 1) << 5) | (((lane >> 5) & 1) << 8); }
; template <int OFF> __device__ __forceinline__ s16x4 tr_read(int vb) {
;   s16x4 r; asm volatile("ds_read_b64_tr_b16 %0, %1 offset:%2" : "=&v"(r) : "v"(vb), "i"(OFF) : "memory"); return r;
; }
; template <int D0> __device__ __forceinline__ void pv_one(f32x16& od, int vb, bf16x8 pa0, bf16x8 pa1, bf16x8 pa2, bf16x8 pa3) {
;   const s16x4 l0 = tr_read<v_rd_off(D0, 0, 0)>(vb), h0 = tr_read<v_rd_off(D0, 0, 1)>(vb), l1 = tr_read<v_rd_off(D0, 1, 0)>(vb), h1 = tr_read<v_rd_off(D0, 1, 1)>(vb);
; template <int DQK, int MODE, int ldq, int ldk, int ldv> ...
;     ...
;     SBAR(); qkt<DQK>(pB0, pB1, K_lds + SHM_K, qr, r32, hi);
;     finishSM(pA0, pA1, alA, l_reg, pa0, pa1, pa2, pa3); SBAR();
;     SLOAD(SO, j + 2); SBAR();
;     pv_d0(o, vb0, pa0, pa1, pa2, pa3); BIAS(pB0, pB1, j); partialSM<DQK>(pB0, pB1, m_reg, mnB, alB);
.Lmy_h1B:
	s_waitcnt vmcnt(0)
	ds_write_b128 v146, v[88:91] offset:32768
	ds_write_b128 v145, v[92:95] offset:16384
	v_cvt_pk_bf16_f32 v200, v126, v160
	v_cvt_pk_bf16_f32 v201, v127, v161
	v_cvt_pk_bf16_f32 v202, v158, v162
	v_cvt_pk_bf16_f32 v203, v159, v163
	v_cvt_pk_bf16_f32 v226, v118, v121
	v_cvt_pk_bf16_f32 v227, v119, v122
	v_cvt_pk_bf16_f32 v228, v120, v123
	v_cvt_pk_bf16_f32 v229, v124, v125
	v_cvt_pk_bf16_f32 v230, v114, v115
	v_cvt_pk_bf16_f32 v231, v112, v113
	v_cvt_pk_bf16_f32 v232, v108, v109
	v_cvt_pk_bf16_f32 v233, v104, v105
	v_cvt_pk_bf16_f32 v136, v102, v103
	v_cvt_pk_bf16_f32 v137, v110, v111
	v_cvt_pk_bf16_f32 v138, v106, v107
	v_cvt_pk_bf16_f32 v139, v100, v101
	v_add_f32_e32 v155, v126, v160
	v_add_f32_e32 v155, v127, v155
	v_add_f32_e32 v155, v161, v155
	v_add_f32_e32 v155, v158, v155
	v_add_f32_e32 v155, v162, v155
	v_add_f32_e32 v155, v159, v155
	v_add_f32_e32 v155, v163, v155
	v_add_f32_e32 v155, v118, v155
	v_add_f32_e32 v155, v121, v155
	v_add_f32_e32 v155, v119, v155
	v_add_f32_e32 v155, v122, v155
	v_add_f32_e32 v155, v120, v155
	v_add_f32_e32 v155, v123, v155
	v_add_f32_e32 v155, v124, v155
	v_add_f32_e32 v155, v125, v155
	v_add_f32_e32 v155, v114, v155
	v_add_f32_e32 v155, v115, v155
	v_add_f32_e32 v155, v112, v155
	v_add_f32_e32 v155, v113, v155
	v_add_f32_e32 v155, v108, v155
	v_add_f32_e32 v155, v109, v155
	v_add_f32_e32 v155, v104, v155
	v_add_f32_e32 v155, v105, v155
	v_add_f32_e32 v155, v102, v155
	v_add_f32_e32 v155, v103, v155
	v_add_f32_e32 v155, v110, v155
	v_add_f32_e32 v155, v111, v155
	v_add_f32_e32 v155, v106, v155
	v_add_f32_e32 v155, v107, v155
	v_add_f32_e32 v155, v100, v155
	v_add_f32_e32 v155, v101, v155
	s_lshl_b32 s0, s11, 6
	s_cmpk_lt_u32 s25, 0x7e
	s_cselect_b32 s1, s10, s24
	s_add_i32 s1, s1, s0
	s_addk_i32 s1, 0xffc0
	s_mul_i32 s1, s1, 0x300
	s_add_u32 s12, s18, s1
	s_addc_u32 s13, s19, 0
	s_cmpk_lt_u32 s25, 0x7f
	s_cselect_b32 s98, s10, s24
	s_add_i32 s98, s98, s0
	s_addk_i32 s98, 0xff80
	s_lshl_b32 s98, s98, 9
	s_add_u32 s98, s20, s98
	s_addc_u32 s99, s21, 0
	global_load_dwordx4 v[100:103], v134, s[12:13]
	global_load_dwordx4 v[108:111], v135, s[98:99]
	ds_read_b128 v[32:35], v148 offset:49152
	ds_read_b128 v[36:39], v148 offset:57344
	ds_read_b128 v[164:167], v152 offset:49152
	ds_read_b128 v[168:171], v152 offset:57344
	s_waitcnt lgkmcnt(3)
	v_mfma_f32_32x32x16_bf16 v[48:63], v[32:35], v[84:87], v[210:225]
	s_waitcnt lgkmcnt(2)
	v_mfma_f32_32x32x16_bf16 v[32:47], v[36:39], v[84:87], v[210:225]
	s_waitcnt lgkmcnt(1)
	v_mfma_f32_32x32x16_bf16 v[48:63], v[164:167], v[80:83], v[48:63]
	s_waitcnt lgkmcnt(0)
	v_mfma_f32_32x32x16_bf16 v[32:47], v[168:171], v[80:83], v[32:47]
	ds_read_b128 v[164:167], v151 offset:49152
	ds_read_b128 v[168:171], v151 offset:57344
	s_waitcnt lgkmcnt(1)
	v_mfma_f32_32x32x16_bf16 v[48:63], v[164:167], v[76:79], v[48:63]
	s_waitcnt lgkmcnt(0)
	v_mfma_f32_32x32x16_bf16 v[32:47], v[168:171], v[76:79], v[32:47]
	ds_read_b128 v[164:167], v149 offset:49152
	ds_read_b128 v[168:171], v149 offset:57344
	s_waitcnt lgkmcnt(1)
	v_mfma_f32_32x32x16_bf16 v[48:63], v[164:167], v[72:75], v[48:63]
	s_waitcnt lgkmcnt(0)
	v_mfma_f32_32x32x16_bf16 v[32:47], v[168:171], v[72:75], v[32:47]
	ds_read_b128 v[164:167], v150 offset:49152
	ds_read_b128 v[168:171], v150 offset:57344
	s_waitcnt lgkmcnt(1)
	v_mfma_f32_32x32x16_bf16 v[48:63], v[164:167], v[68:71], v[48:63]
	s_waitcnt lgkmcnt(0)
	v_mfma_f32_32x32x16_bf16 v[32:47], v[168:171], v[68:71], v[32:47]
	ds_read_b128 v[164:167], v153 offset:49152
	ds_read_b128 v[168:171], v153 offset:57344
	s_waitcnt lgkmcnt(1)
	v_mfma_f32_32x32x16_bf16 v[48:63], v[164:167], v[64:67], v[48:63]
	s_waitcnt lgkmcnt(0)
	v_mfma_f32_32x32x16_bf16 v[32:47], v[168:171], v[64:67], v[32:47]
	ds_read_b64_tr_b16 v[184:185], v144 offset:0
	ds_read_b64_tr_b16 v[186:187], v144 offset:0x800
	ds_read_b64_tr_b16 v[188:189], v144 offset:0x1000
	ds_read_b64_tr_b16 v[190:191], v144 offset:0x1800
	ds_read_b64_tr_b16 v[192:193], v144 offset:0x2000
	ds_read_b64_tr_b16 v[194:195], v144 offset:0x2800
	ds_read_b64_tr_b16 v[196:197], v144 offset:0x3000
	ds_read_b64_tr_b16 v[198:199], v144 offset:0x3800
	s_waitcnt lgkmcnt(0)
	s_nop 0
	v_mfma_f32_32x32x16_bf16 v[0:15], v[200:203], v[184:187], v[0:15]
	ds_read_b64_tr_b16 v[184:185], v144 offset:0x200
	ds_read_b64_tr_b16 v[186:187], v144 offset:0xa00
	v_mfma_f32_32x32x16_bf16 v[0:15], v[226:229], v[188:191], v[0:15]
	ds_read_b64_tr_b16 v[188:189], v144 offset:0x1200
	ds_read_b64_tr_b16 v[190:191], v144 offset:0x1a00
	v_mfma_f32_32x32x16_bf16 v[0:15], v[230:233], v[192:195], v[0:15]
	ds_read_b64_tr_b16 v[192:193], v144 offset:0x2200
	ds_read_b64_tr_b16 v[194:195], v144 offset:0x2a00
	v_mfma_f32_32x32x16_bf16 v[0:15], v[136:139], v[196:199], v[0:15]
	ds_read_b64_tr_b16 v[196:197], v144 offset:0x3200
	ds_read_b64_tr_b16 v[198:199], v144 offset:0x3a00
	s_waitcnt lgkmcnt(0)
	v_mfma_f32_32x32x16_bf16 v[16:31], v[200:203], v[184:187], v[16:31]
	v_mfma_f32_32x32x16_bf16 v[16:31], v[226:229], v[188:191], v[16:31]
	v_mfma_f32_32x32x16_bf16 v[16:31], v[230:233], v[192:195], v[16:31]
	v_mfma_f32_32x32x16_bf16 v[16:31], v[136:139], v[196:199], v[16:31]
	v_max_f32_e32 v112, v48, v49
	v_max3_f32 v112, v112, v50, v51
	v_max3_f32 v112, v112, v52, v53
	v_max3_f32 v112, v112, v54, v55
	v_max3_f32 v112, v112, v56, v57
	v_max3_f32 v112, v112, v58, v59
	v_max3_f32 v112, v112, v60, v61
	v_max3_f32 v112, v112, v62, v63
	v_max3_f32 v112, v112, v32, v33
	v_max3_f32 v112, v112, v34, v35
	v_max3_f32 v112, v112, v36, v37
	v_max3_f32 v112, v112, v38, v39
	v_max3_f32 v112, v112, v40, v41
	v_max3_f32 v112, v112, v42, v43
	v_max3_f32 v112, v112, v44, v45
	v_max3_f32 v112, v112, v46, v47
	v_cmp_ge_f32_e32 vcc, s80, v112
	s_cmp_eq_u64 vcc, exec
	s_cbranch_scc0 .Lmy_rare_b1
	v_mov_b32_e32 v157, 1.0
	s_mov_b64 vcc, 0

; #define SBAR() __builtin_amdgcn_sched_barrier(0)
; __device__ __forceinline__ void finishSM(f32x16& p0, f32x16& p1, float alpha, float& l_reg, bf16x8& pa0, bf16x8& pa1, bf16x8& pa2, bf16x8& pa3) {
; #pragma unroll
;   for (int r = 0; r < 16; ++r) p1[r] = __builtin_amdgcn_exp2f(p1[r]);
;   float ps = 0;
; #pragma unroll
;   for (int r = 0; r < 16; ++r) ps += p0[r];
; #pragma unroll
;   for (int r = 0; r < 16; ++r) ps += p1[r];
;   { auto rr = __builtin_amdgcn_permlane32_swap(__float_as_uint(ps), __float_as_uint(ps), false, false);
;     ps = __uint_as_float(rr[0]) + __uint_as_float(rr[1]); }
;   l_reg = l_reg * alpha + ps;
;     ...
;   PK4(p0, 0, pa0); PK4(p0, 8, pa1); PK4(p1, 0, pa2); PK4(p1, 8, pa3);
;     ...
; }
; template <int DQK> __device__ __forceinline__ void qkt(f32x16& p0, f32x16& p1, const char* Ks, const bf16x8* qr, int r32, int hi) {
;   p0 = f32x16{}; p1 = f32x16{};
; #pragma unroll
;   for (int d0 = 0; d0 < DQK / 16; ++d0) { int cb = (d0 * 16 + hi * 8) * 2;
;     bf16x8 b0 = *reinterpret_cast<const bf16x8*>(Ks + KSWZ(r32, cb));
;     bf16x8 b1 = *reinterpret_cast<const bf16x8*>(Ks + KSWZ(32 + r32, cb));
;     p0 = __builtin_amdgcn_mfma_f32_32x32x16_bf16(b0, qr[d0], p0, 0, 0, 0);
;     p1 = __builtin_amdgcn_mfma_f32_32x32x16_bf16(b1, qr[d0], p1, 0, 0, 0); }
; }
; __device__ __forceinline__ int v_st(int k, int c) { const int kk = (k & ~0xC) | ((k & 4) << 1) | ((k & 8) >> 1); return ((kk >> 3) * 4 + (c >> 5)) * 512 + ((kk & 7) * 32 + (c & 31)) * 2; }
; __device__ __forceinline__ int v_rd_base(int lane) { return ((lane & 3) << 3) | (((lane >> 2) & 3) << 6) | (((lane >> 4) & 1) << 5) | (((lane >> 5) & 1) << 8); }
; template <int OFF> __device__ __forceinline__ s16x4 tr_read(int vb) {
;   s16x4 r; asm volatile("ds_read_b64_tr_b16 %0, %1 offset:%2" : "=&v"(r) : "v"(vb), "i"(OFF) : "memory"); return r;
; }
; template <int D0> __device__ __forceinline__ void pv_one(f32x16& od, int vb, bf16x8 pa0, bf16x8 pa1, bf16x8 pa2, bf16x8 pa3) {
; template <int DQK, int MODE, int ldq, int ldk, int ldv> ...
;     ...
;     SBAR(); qkt<DQK>(pA0, pA1, K_lds, qr, r32, hi);
;     finishSM(pB0, pB1, alB, l_reg, pa0, pa1, pa2, pa3); SBAR();
;     if (j + 3 < NT) SLOAD(SE, j + 3); SBAR();
;     pv_d0(o, vb0 + (int)SHM_V, pa0, pa1, pa2, pa3); BIAS(pA0, pA1, j + 1); partialSM<DQK>(pA0, pA1, m_reg, mnA, alA);
.Lmy_h2B_306:
	ds_read_b128 v[32:35], v148 offset:32768
	ds_read_b128 v[36:39], v148 offset:40960
	ds_read_b128 v[176:179], v152 offset:32768
	ds_read_b128 v[180:183], v152 offset:40960
	s_waitcnt lgkmcnt(3)
	v_mfma_f32_32x32x16_bf16 v[48:63], v[32:35], v[84:87], v[210:225]
	s_waitcnt lgkmcnt(2)
	v_mfma_f32_32x32x16_bf16 v[32:47], v[36:39], v[84:87], v[210:225]
	s_waitcnt lgkmcnt(1)
	v_mfma_f32_32x32x16_bf16 v[48:63], v[176:179], v[80:83], v[48:63]
	s_waitcnt lgkmcnt(0)
	v_mfma_f32_32x32x16_bf16 v[32:47], v[180:183], v[80:83], v[32:47]
	ds_read_b128 v[176:179], v151 offset:32768
	ds_read_b128 v[180:183], v151 offset:40960
	s_waitcnt lgkmcnt(1)
	v_mfma_f32_32x32x16_bf16 v[48:63], v[176:179], v[76:79], v[48:63]
	s_waitcnt lgkmcnt(0)
	v_mfma_f32_32x32x16_bf16 v[32:47], v[180:183], v[76:79], v[32:47]
	ds_read_b128 v[176:179], v149 offset:32768
	ds_read_b128 v[180:183], v149 offset:40960
	s_waitcnt lgkmcnt(1)
	v_mfma_f32_32x32x16_bf16 v[48:63], v[176:179], v[72:75], v[48:63]
	s_waitcnt lgkmcnt(0)
	v_mfma_f32_32x32x16_bf16 v[32:47], v[180:183], v[72:75], v[32:47]
	ds_read_b128 v[176:179], v150 offset:32768
	ds_read_b128 v[180:183], v150 offset:40960
	s_waitcnt lgkmcnt(1)
	v_mfma_f32_32x32x16_bf16 v[48:63], v[176:179], v[68:71], v[48:63]
	s_waitcnt lgkmcnt(0)
	v_mfma_f32_32x32x16_bf16 v[32:47], v[180:183], v[68:71], v[32:47]
	ds_read_b128 v[176:179], v153 offset:32768
	ds_read_b128 v[180:183], v153 offset:40960
	s_waitcnt lgkmcnt(1)
	v_mfma_f32_32x32x16_bf16 v[48:63], v[176:179], v[64:67], v[48:63]
	s_waitcnt lgkmcnt(0)
	v_mfma_f32_32x32x16_bf16 v[32:47], v[180:183], v[64:67], v[32:47]
	ds_read_b64_tr_b16 v[184:185], v143 offset:0
	ds_read_b64_tr_b16 v[186:187], v143 offset:0x800
	ds_read_b64_tr_b16 v[188:189], v143 offset:0x1000
	ds_read_b64_tr_b16 v[190:191], v143 offset:0x1800
	ds_read_b64_tr_b16 v[192:193], v143 offset:0x2000
	ds_read_b64_tr_b16 v[194:195], v143 offset:0x2800
	ds_read_b64_tr_b16 v[196:197], v143 offset:0x3000
	ds_read_b64_tr_b16 v[198:199], v143 offset:0x3800
	s_waitcnt lgkmcnt(0)
	s_nop 0
	v_mfma_f32_32x32x16_bf16 v[0:15], v[200:203], v[184:187], v[0:15]
	ds_read_b64_tr_b16 v[184:185], v143 offset:0x200
	ds_read_b64_tr_b16 v[186:187], v143 offset:0xa00
	v_mfma_f32_32x32x16_bf16 v[0:15], v[226:229], v[188:191], v[0:15]
	ds_read_b64_tr_b16 v[188:189], v143 offset:0x1200
	ds_read_b64_tr_b16 v[190:191], v143 offset:0x1a00
	v_mfma_f32_32x32x16_bf16 v[0:15], v[230:233], v[192:195], v[0:15]
	ds_read_b64_tr_b16 v[192:193], v143 offset:0x2200
	ds_read_b64_tr_b16 v[194:195], v143 offset:0x2a00
	v_mfma_f32_32x32x16_bf16 v[0:15], v[136:139], v[196:199], v[0:15]
	ds_read_b64_tr_b16 v[196:197], v143 offset:0x3200
	ds_read_b64_tr_b16 v[198:199], v143 offset:0x3a00
	s_waitcnt lgkmcnt(0)
	v_mfma_f32_32x32x16_bf16 v[16:31], v[200:203], v[184:187], v[16:31]
	v_mfma_f32_32x32x16_bf16 v[16:31], v[226:229], v[188:191], v[16:31]
	v_mfma_f32_32x32x16_bf16 v[16:31], v[230:233], v[192:195], v[16:31]
	v_mfma_f32_32x32x16_bf16 v[16:31], v[136:139], v[196:199], v[16:31]
	v_max_f32_e32 v112, v48, v49
	v_max3_f32 v112, v112, v50, v51
	v_max3_f32 v112, v112, v52, v53
	v_max3_f32 v112, v112, v54, v55
	v_max3_f32 v112, v112, v56, v57
	v_max3_f32 v112, v112, v58, v59
	v_max3_f32 v112, v112, v60, v61
	v_max3_f32 v112, v112, v62, v63
	v_max3_f32 v112, v112, v32, v33
	v_max3_f32 v112, v112, v34, v35
	v_max3_f32 v112, v112, v36, v37
	v_max3_f32 v112, v112, v38, v39
	v_max3_f32 v112, v112, v40, v41
	v_max3_f32 v112, v112, v42, v43
	v_max3_f32 v112, v112, v44, v45
	v_max3_f32 v112, v112, v46, v47
	v_cmp_ge_f32_e32 vcc, s80, v112
	s_cmp_eq_u64 vcc, exec
	s_cbranch_scc0 .Lmy_rare_b2
	v_mov_b32_e32 v117, 1.0
	s_mov_b64 vcc, 0
